# ATTN far tiles: QK chain per 32-key half, exp2 of the first half under the second half's MFMAs, PV under the second half's exp2; V fragments read early (LDS counter kept <= 15)
# baseline (speedup 1.0000x reference)
.Lattn_fast:
	v_add_u32_e32 v149, s5, v140
	v_add_u32_e32 v150, s5, v141
	v_add_u32_sdwa v230, v4, s25 dst_sel:DWORD dst_unused:UNUSED_PAD src0_sel:BYTE_0 src1_sel:DWORD
	v_add_u32_sdwa v231, v4, s25 dst_sel:DWORD dst_unused:UNUSED_PAD src0_sel:BYTE_1 src1_sel:DWORD
	v_add_u32_sdwa v232, v4, s25 dst_sel:DWORD dst_unused:UNUSED_PAD src0_sel:BYTE_2 src1_sel:DWORD
	v_add_u32_sdwa v233, v4, s25 dst_sel:DWORD dst_unused:UNUSED_PAD src0_sel:BYTE_3 src1_sel:DWORD
	ds_read_b128 v[66:69], v230
	ds_read_b128 v[70:73], v231
	ds_read_b128 v[74:77], v232
	ds_read_b128 v[78:81], v233
	ds_read_b128 v[182:185], v149
	ds_read_b128 v[186:189], v149 offset:2048
	ds_read_b128 v[190:193], v149 offset:4096
	ds_read_b128 v[194:197], v149 offset:6144
	v_add_u32_sdwa v234, v3, s25 dst_sel:DWORD dst_unused:UNUSED_PAD src0_sel:BYTE_0 src1_sel:DWORD
	v_add_u32_sdwa v235, v3, s25 dst_sel:DWORD dst_unused:UNUSED_PAD src0_sel:BYTE_1 src1_sel:DWORD
	v_add_u32_sdwa v236, v3, s25 dst_sel:DWORD dst_unused:UNUSED_PAD src0_sel:BYTE_2 src1_sel:DWORD
	v_add_u32_sdwa v237, v3, s25 dst_sel:DWORD dst_unused:UNUSED_PAD src0_sel:BYTE_3 src1_sel:DWORD
	s_waitcnt lgkmcnt(3)
	v_mfma_f32_32x32x16_bf16 v[66:81], v[182:185], v[110:113], v[66:81]
	ds_read_b128 v[82:85], v234
	ds_read_b128 v[86:89], v235
	ds_read_b128 v[90:93], v236
	ds_read_b128 v[94:97], v237
	ds_read_b128 v[198:201], v149 offset:512
	ds_read_b128 v[202:205], v149 offset:2560
	ds_read_b128 v[206:209], v149 offset:4608
	ds_read_b128 v[210:213], v149 offset:6656
	s_waitcnt lgkmcnt(10)
	v_mfma_f32_32x32x16_bf16 v[66:81], v[186:189], v[98:101], v[66:81]
	s_waitcnt lgkmcnt(9)
	v_mfma_f32_32x32x16_bf16 v[66:81], v[190:193], v[102:105], v[66:81]
	s_waitcnt lgkmcnt(8)
	v_mfma_f32_32x32x16_bf16 v[66:81], v[194:197], v[106:109], v[66:81]
	s_waitcnt lgkmcnt(3)
	v_mfma_f32_32x32x16_bf16 v[82:97], v[198:201], v[110:113], v[82:97]
	s_waitcnt lgkmcnt(2)
	v_mfma_f32_32x32x16_bf16 v[82:97], v[202:205], v[98:101], v[82:97]
	ds_read_b64_tr_b16 v[152:153], v150
	ds_read_b64_tr_b16 v[154:155], v150 offset:512
	ds_read_b64_tr_b16 v[156:157], v150 offset:1024
	ds_read_b64_tr_b16 v[158:159], v150 offset:1536
	ds_read_b64_tr_b16 v[160:161], v150 offset:2048
	ds_read_b64_tr_b16 v[162:163], v150 offset:2560
	ds_read_b64_tr_b16 v[164:165], v150 offset:3072
	ds_read_b64_tr_b16 v[166:167], v150 offset:3584
	v_exp_f32_e32 v66, v66
	v_exp_f32_e32 v67, v67
	v_exp_f32_e32 v68, v68
	v_exp_f32_e32 v69, v69
	s_waitcnt lgkmcnt(9)
	v_mfma_f32_32x32x16_bf16 v[82:97], v[206:209], v[102:105], v[82:97]
	v_exp_f32_e32 v70, v70
	v_exp_f32_e32 v71, v71
	v_exp_f32_e32 v72, v72
	v_exp_f32_e32 v73, v73
	s_waitcnt lgkmcnt(8)
	v_mfma_f32_32x32x16_bf16 v[82:97], v[210:213], v[106:109], v[82:97]
	v_exp_f32_e32 v74, v74
	v_exp_f32_e32 v75, v75
	v_exp_f32_e32 v76, v76
	v_exp_f32_e32 v77, v77
	v_exp_f32_e32 v78, v78
	v_exp_f32_e32 v79, v79
	v_exp_f32_e32 v80, v80
	v_exp_f32_e32 v81, v81
	s_waitcnt lgkmcnt(7)
	ds_read_b64_tr_b16 v[168:169], v150 offset:4096
	ds_read_b64_tr_b16 v[170:171], v150 offset:4608
	ds_read_b64_tr_b16 v[172:173], v150 offset:5120
	ds_read_b64_tr_b16 v[174:175], v150 offset:5632
	ds_read_b64_tr_b16 v[214:215], v150 offset:6144
	ds_read_b64_tr_b16 v[216:217], v150 offset:6656
	ds_read_b64_tr_b16 v[218:219], v150 offset:7168
	ds_read_b64_tr_b16 v[220:221], v150 offset:7680
	v_cvt_pk_bf16_f32 v4, v66, v67
	v_cvt_pk_bf16_f32 v5, v68, v69
	v_cvt_pk_bf16_f32 v6, v70, v71
	v_cvt_pk_bf16_f32 v7, v72, v73
	v_cvt_pk_bf16_f32 v8, v74, v75
	v_cvt_pk_bf16_f32 v9, v76, v77
	v_cvt_pk_bf16_f32 v10, v78, v79
	v_cvt_pk_bf16_f32 v11, v80, v81
	s_waitcnt lgkmcnt(8)
	v_mfma_f32_32x32x16_bf16 v[34:49], v[4:7], v[152:155], v[34:49]
	v_exp_f32_e32 v82, v82
	v_exp_f32_e32 v83, v83
	v_exp_f32_e32 v84, v84
	s_waitcnt lgkmcnt(6)
	v_mfma_f32_32x32x16_bf16 v[18:33], v[4:7], v[168:171], v[18:33]
	v_exp_f32_e32 v85, v85
	v_exp_f32_e32 v86, v86
	v_exp_f32_e32 v87, v87
	v_mfma_f32_32x32x16_bf16 v[50:65], v[4:7], v[226:229], v[50:65]
	v_exp_f32_e32 v88, v88
	v_exp_f32_e32 v89, v89
	v_exp_f32_e32 v90, v90
	v_mfma_f32_32x32x16_bf16 v[34:49], v[8:11], v[156:159], v[34:49]
	v_exp_f32_e32 v91, v91
	v_exp_f32_e32 v92, v92
	v_exp_f32_e32 v93, v93
	s_waitcnt lgkmcnt(4)
	v_mfma_f32_32x32x16_bf16 v[18:33], v[8:11], v[172:175], v[18:33]
	v_exp_f32_e32 v94, v94
	v_exp_f32_e32 v95, v95
	v_exp_f32_e32 v96, v96
	v_exp_f32_e32 v97, v97
	v_mfma_f32_32x32x16_bf16 v[50:65], v[8:11], v[226:229], v[50:65]
	v_cvt_pk_bf16_f32 v12, v82, v83
	v_cvt_pk_bf16_f32 v13, v84, v85
	v_cvt_pk_bf16_f32 v14, v86, v87
	v_cvt_pk_bf16_f32 v15, v88, v89
	v_cvt_pk_bf16_f32 v222, v90, v91
	v_cvt_pk_bf16_f32 v223, v92, v93
	v_cvt_pk_bf16_f32 v224, v94, v95
	v_cvt_pk_bf16_f32 v225, v96, v97
	s_nop 1
	v_mfma_f32_32x32x16_bf16 v[34:49], v[12:15], v[160:163], v[34:49]
	s_waitcnt lgkmcnt(2)
	v_mfma_f32_32x32x16_bf16 v[18:33], v[12:15], v[214:217], v[18:33]
	v_mfma_f32_32x32x16_bf16 v[50:65], v[12:15], v[226:229], v[50:65]
	v_mfma_f32_32x32x16_bf16 v[34:49], v[222:225], v[164:167], v[34:49]
	s_waitcnt lgkmcnt(0)
	v_mfma_f32_32x32x16_bf16 v[18:33], v[222:225], v[218:221], v[18:33]
	v_mfma_f32_32x32x16_bf16 v[50:65], v[222:225], v[226:229], v[50:65]
	s_branch .LBB0_954
